# RG-LRU finalize gate GEMM: direction 0's ks2/ks3 weight slices requested with ks0/ks1, direction 1's per-channel parameters requested with direction 0's (on top of the output-stage load batching)
# speedup vs baseline: 1.0056x; 1.0056x over previous
; #define MFMA(a, b, c) __builtin_amdgcn_mfma_f32_32x32x16_bf16((a), (b), (c), 0, 0, 0)
; DI u16 f2bf(float x) { return (u16)(pack2(x, 0.f) & 0xffffu); }
; DI float bf2f(u16 v) { return __uint_as_float(((unsigned)v) << 16); }
; DI void lru_item(const Params& p, int l, int b, int chunk, int blk, bool fin, char* smem, int tid) {
;     ...
;   {
;     const int ch = tid & 63;
;     const float* cw = p.cw + (size_t)l * 4 * 256 + c0 + ch;
;     const float w0 = cw[0], w1 = cw[256], w2 = cw[512], w3 = cw[768], bias = p.cb[l * 256 + c0 + ch];
; #pragma unroll 4
;     for (int e = 0; e < 16; e++) {
;       const int t = (tid >> 6) + 4 * e;
;       float v = w0 * bf2f(xr[t * 64 + ch]) + w1 * bf2f(xr[(t + 1) * 64 + ch]) + w2 * bf2f(xr[(t + 2) * 64 + ch]) + w3 * bf2f(xr[(t + 3) * 64 + ch]) + bias;
;       xcb[t][ch] = f2bf(v);
;     }
;   }
;   __syncthreads();
;   {
;     const int tb = w & 1, ob = w >> 1;
;     const int chn = ob * 32 + r;
; #pragma unroll
;     for (int dir = 0; dir < 2; dir++) {
;       f32x16 ga, gx;
; #pragma unroll
;       for (int i = 0; i < 16; i++) { ga[i] = 0.f; gx[i] = 0.f; }
;       const u16* wa = p.WtA + (((size_t)l * 2 + dir) * 4 + blk) * 4096 + (size_t)chn * 64 + h * 8;
;       const u16* wx = p.WtX + (((size_t)l * 2 + dir) * 4 + blk) * 4096 + (size_t)chn * 64 + h * 8;
; #pragma unroll
;       for (int ks = 0; ks < 4; ks++) {
;         bf16x8 a = *(const bf16x8*)&xcb[tb * 32 + r][ks * 16 + h * 8];
;         bf16x8 ba = *(const bf16x8*)(wa + ks * 16), bx = *(const bf16x8*)(wx + ks * 16);
;         ga = MFMA(a, ba, ga); gx = MFMA(a, bx, gx);
;       }
;       const int pi = (l * 2 + dir) * 256 + c0 + chn;
;       const float b_a = p.ba[pi], b_x = p.bx[pi], lam = p.lam[pi];
.LBB0_1049:
	ds_read_u16 v7, v6 offset:9216
	ds_read_u16 v8, v6 offset:9344
	ds_read_u16 v11, v6 offset:9472
	ds_read_u16 v12, v6 offset:9600
	v_add_u32_e32 v14, s0, v60
	s_addk_i32 s0, 0x900
	s_waitcnt lgkmcnt(2)
	v_lshlrev_b32_e32 v9, 16, v8
	v_lshlrev_b32_e32 v8, 16, v7
	s_waitcnt lgkmcnt(0)
	v_lshlrev_b32_e32 v13, 16, v12
	v_lshlrev_b32_e32 v12, 16, v11
	s_waitcnt vmcnt(3)
	v_pk_mul_f32 v[8:9], v[2:3], v[8:9]
	s_waitcnt vmcnt(1)
	v_pk_mul_f32 v[12:13], v[4:5], v[12:13]
	v_add_f32_e32 v7, v8, v9
	v_add_f32_e32 v7, v7, v12
	v_add_f32_e32 v7, v7, v13
	s_waitcnt vmcnt(0)
	v_add_f32_e32 v7, v0, v7
	v_cvt_pk_bf16_f32 v7, v7, s0
	ds_write_b16 v14, v7
	ds_read_u16 v7, v6 offset:9856
	ds_read_u16 v11, v6 offset:9984
	ds_read_u16 v8, v6 offset:9728
	ds_read_u16 v12, v6 offset:10112
	s_cmpk_eq_i32 s0, 0x2400
	s_waitcnt lgkmcnt(3)
	v_lshlrev_b32_e32 v9, 16, v7
	s_waitcnt lgkmcnt(1)
	v_lshlrev_b32_e32 v8, 16, v8
	s_waitcnt lgkmcnt(0)
	v_lshlrev_b32_e32 v13, 16, v12
	v_lshlrev_b32_e32 v12, 16, v11
	v_pk_mul_f32 v[8:9], v[2:3], v[8:9]
	v_pk_mul_f32 v[12:13], v[4:5], v[12:13]
	v_add_f32_e32 v7, v8, v9
	v_add_f32_e32 v7, v7, v12
	v_add_f32_e32 v7, v7, v13
	v_add_f32_e32 v7, v0, v7
	v_cvt_pk_bf16_f32 v7, v7, s0
	ds_write_b16 v14, v7 offset:576
	ds_read_u16 v7, v6 offset:10368
	ds_read_u16 v11, v6 offset:10496
	ds_read_u16 v8, v6 offset:10240
	ds_read_u16 v12, v6 offset:10624
	s_waitcnt lgkmcnt(3)
	v_lshlrev_b32_e32 v9, 16, v7
	s_waitcnt lgkmcnt(1)
	v_lshlrev_b32_e32 v8, 16, v8
	s_waitcnt lgkmcnt(0)
	v_lshlrev_b32_e32 v13, 16, v12
	v_lshlrev_b32_e32 v12, 16, v11
	v_pk_mul_f32 v[8:9], v[2:3], v[8:9]
	v_pk_mul_f32 v[12:13], v[4:5], v[12:13]
	v_add_f32_e32 v7, v8, v9
	v_add_f32_e32 v7, v7, v12
	v_add_f32_e32 v7, v7, v13
	v_add_f32_e32 v7, v0, v7
	v_cvt_pk_bf16_f32 v7, v7, s0
	ds_write_b16 v14, v7 offset:1152
	ds_read_u16 v7, v6 offset:10880
	ds_read_u16 v11, v6 offset:11008
	ds_read_u16 v8, v6 offset:10752
	ds_read_u16 v12, v6 offset:11136
	v_add_u32_e32 v6, 0x800, v6
	s_waitcnt lgkmcnt(3)
	v_lshlrev_b32_e32 v9, 16, v7
	s_waitcnt lgkmcnt(1)
	v_lshlrev_b32_e32 v8, 16, v8
	s_waitcnt lgkmcnt(0)
	v_lshlrev_b32_e32 v13, 16, v12
	v_lshlrev_b32_e32 v12, 16, v11
	v_pk_mul_f32 v[8:9], v[2:3], v[8:9]
	v_pk_mul_f32 v[12:13], v[4:5], v[12:13]
	v_add_f32_e32 v7, v8, v9
	v_add_f32_e32 v7, v7, v12
	v_add_f32_e32 v7, v7, v13
	v_add_f32_e32 v7, v0, v7
	v_cvt_pk_bf16_f32 v7, v7, s0
	ds_write_b16 v14, v7 offset:1728
	s_cbranch_scc0 .LBB0_1049
	v_lshl_or_b32 v2, v10, 12, s16
	v_mov_b32_e32 v3, s17
	v_lshlrev_b64 v[80:81], 1, v[2:3]
	v_lshl_add_u64 v[114:115], v[54:55], 0, v[80:81]
	s_waitcnt lgkmcnt(0)
	s_barrier
	v_lshl_add_u64 v[116:117], v[56:57], 0, v[80:81]
	global_load_dwordx4 v[2:5], v[114:115], off
	global_load_dwordx4 v[6:9], v[116:117], off
	ds_read_b128 v[10:13], v87
	ds_read_b128 v[82:85], v87 offset:32
	global_load_dwordx4 v[106:109], v[114:115], off offset:32
	global_load_dwordx4 v[110:113], v[116:117], off offset:32
	global_load_dwordx4 v[122:125], v[114:115], off offset:64
	global_load_dwordx4 v[126:129], v[116:117], off offset:64
	global_load_dwordx4 v[130:133], v[114:115], off offset:96
	global_load_dwordx4 v[134:137], v[116:117], off offset:96
	v_or_b32_e32 v0, s94, v74
	v_add_u32_e32 v78, v0, v38
	v_ashrrev_i32_e32 v79, 31, v78
	v_readlane_b32 s52, v252, 16
	v_lshlrev_b64 v[78:79], 2, v[78:79]
	v_readlane_b32 s53, v252, 17
	v_readlane_b32 s54, v252, 18
	v_readlane_b32 s55, v252, 19
	v_readlane_b32 s56, v252, 20
	v_readlane_b32 s57, v252, 21
	v_readlane_b32 s58, v252, 22
	v_readlane_b32 s59, v252, 23
	v_readlane_b32 s60, v252, 24
	v_readlane_b32 s61, v252, 25
	v_readlane_b32 s62, v252, 26
	v_readlane_b32 s63, v252, 27
	v_readlane_b32 s64, v252, 28
	v_readlane_b32 s65, v252, 29
	v_readlane_b32 s66, v252, 30
	v_readlane_b32 s67, v252, 31
	s_mov_b32 s2, 0x3f2aaaab
	s_mov_b32 s3, 0x3f317218
	s_mov_b32 s20, 0x7f800000
	s_mov_b32 s21, 0x33800000
	s_mov_b32 s24, 0xc1000000
	s_mov_b32 s22, 0xbe800000
	v_or_b32_e32 v80, 0x8000, v80
	s_waitcnt vmcnt(7) lgkmcnt(1)
	v_mfma_f32_32x32x16_bf16 v[18:33], v[10:13], v[2:5], 0
	s_waitcnt vmcnt(6)
	v_mfma_f32_32x32x16_bf16 v[2:17], v[10:13], v[6:9], 0
	s_waitcnt vmcnt(5) lgkmcnt(0)
	v_mfma_f32_32x32x16_bf16 v[18:33], v[82:85], v[106:109], v[18:33]
	s_waitcnt vmcnt(4)
	v_mfma_f32_32x32x16_bf16 v[2:17], v[82:85], v[110:113], v[2:17]
	ds_read_b128 v[82:85], v87 offset:64
	s_waitcnt vmcnt(3) lgkmcnt(0)
	v_mfma_f32_32x32x16_bf16 v[18:33], v[82:85], v[122:125], v[18:33]
	s_waitcnt vmcnt(2)
	v_mfma_f32_32x32x16_bf16 v[2:17], v[82:85], v[126:129], v[2:17]
	ds_read_b128 v[82:85], v87 offset:96
	s_waitcnt vmcnt(1) lgkmcnt(0)
	v_mfma_f32_32x32x16_bf16 v[18:33], v[82:85], v[130:133], v[18:33]
	s_waitcnt vmcnt(0)
	v_mfma_f32_32x32x16_bf16 v[2:17], v[82:85], v[134:137], v[2:17]
	v_lshl_add_u64 v[82:83], s[66:67], 0, v[78:79]
	v_readlane_b32 s52, v252, 32
	v_readlane_b32 s54, v252, 34
	v_readlane_b32 s55, v252, 35
	v_readlane_b32 s56, v252, 36
	v_readlane_b32 s57, v252, 37
	v_lshl_add_u64 v[84:85], s[54:55], 0, v[78:79]
	global_load_dword v107, v[84:85], off
	v_lshl_add_u64 v[78:79], s[56:57], 0, v[78:79]
	global_load_dword v0, v[78:79], off
	global_load_dword v71, v[82:83], off
	global_load_dword v182, v[82:83], off offset:1024
	global_load_dword v183, v[84:85], off offset:1024
	global_load_dword v186, v[78:79], off offset:1024
	v_readlane_b32 s53, v252, 33
	v_readlane_b32 s58, v252, 38
	v_readlane_b32 s59, v252, 39
	v_readlane_b32 s60, v252, 40
	v_readlane_b32 s61, v252, 41
	v_readlane_b32 s62, v252, 42
	v_readlane_b32 s63, v252, 43
	v_readlane_b32 s64, v252, 44
	v_readlane_b32 s65, v252, 45
	v_readlane_b32 s66, v252, 46
	v_readlane_b32 s67, v252, 47
	s_waitcnt vmcnt(5)
; DI int crow(int i, int h) { return (i & 3) + 8 * (i >> 2) + 4 * h; }
; DI void lru_item(const Params& p, int l, int b, int chunk, int blk, bool fin, char* smem, int tid) {
;     ...
;       const float b_a = p.ba[pi], b_x = p.bx[pi], lam = p.lam[pi];
;       const float sp = log1pf(__expf(-lam));
; #pragma unroll
;       for (int i = 0; i < 16; i++) {
;         const int tok = tb * 32 + crow(i, h);
;         const float rr = __builtin_amdgcn_rcpf(1.f + __expf(-(ga[i] + b_a))), ii = __builtin_amdgcn_rcpf(1.f + __expf(-(gx[i] + b_x)));
	v_add_f32_e32 v2, v2, v107
	v_mul_f32_e32 v2, 0xbfb8aa3b, v2
	s_waitcnt vmcnt(4)
	v_mul_f32_e32 v0, 0xbfb8aa3b, v0
	v_exp_f32_e32 v0, v0
	v_exp_f32_e32 v2, v2
	s_waitcnt vmcnt(3)
	v_add_f32_e32 v18, v18, v71
	v_mul_f32_e32 v18, 0xbfb8aa3b, v18
	v_add_f32_e32 v106, 1.0, v0
	v_add_f32_e32 v108, -1.0, v106
	v_sub_f32_e32 v109, v108, v106
	v_add_f32_e32 v109, 1.0, v109
	v_sub_f32_e32 v108, v0, v108
	v_add_f32_e32 v110, v108, v109
	v_frexp_mant_f32_e32 v108, v106
	v_cmp_gt_f32_e64 s[0:1], s2, v108
	v_cvt_f64_f32_e32 v[108:109], v106
	v_frexp_exp_i32_f64_e32 v108, v[108:109]
	v_subbrev_co_u32_e64 v116, s[0:1], 0, v108, s[0:1]
	v_sub_u32_e32 v108, 0, v116
	v_ldexp_f32 v106, v106, v108
	v_ldexp_f32 v108, v110, v108
	v_add_f32_e32 v110, -1.0, v106
	v_add_f32_e32 v109, 1.0, v110
	v_sub_f32_e32 v109, v106, v109
	v_add_f32_e32 v111, v108, v109
	v_add_f32_e32 v109, 1.0, v106
	v_add_f32_e32 v112, -1.0, v109
	v_sub_f32_e32 v106, v106, v112
	v_add_f32_e32 v106, v108, v106
	v_add_f32_e32 v117, v109, v106
	v_rcp_f32_e32 v118, v117
	v_sub_f32_e32 v108, v117, v109
	v_add_f32_e32 v109, v110, v111
	v_sub_f32_e32 v106, v106, v108
	v_mul_f32_e32 v120, v109, v118
	v_sub_f32_e32 v108, v109, v110
	v_mul_f32_e32 v110, v117, v120
	v_fma_f32 v112, v120, v117, -v110
	v_fmac_f32_e32 v112, v120, v106
	v_sub_f32_e32 v119, v111, v108
	v_add_f32_e32 v108, v110, v112
	v_sub_f32_e32 v111, v109, v108
	v_pk_add_f32 v[114:115], v[108:109], v[110:111] neg_lo:[0,1] neg_hi:[0,1]
	v_mov_b32_e32 v113, v108
	v_pk_add_f32 v[108:109], v[114:115], v[112:113] neg_lo:[0,1] neg_hi:[0,1]
	v_cmp_neq_f32_e64 s[0:1], s20, v0
	v_add_f32_e32 v109, v119, v109
	v_add_f32_e32 v108, v108, v109
	v_add_f32_e32 v109, v111, v108
	v_mul_f32_e32 v119, v118, v109
	v_mul_f32_e32 v110, v117, v119
	v_fma_f32 v112, v119, v117, -v110
	v_fmac_f32_e32 v112, v119, v106
	v_sub_f32_e32 v106, v111, v109
	v_add_f32_e32 v106, v108, v106
	v_add_f32_e32 v108, v110, v112
	v_sub_f32_e32 v111, v109, v108
	v_pk_add_f32 v[114:115], v[108:109], v[110:111] neg_lo:[0,1] neg_hi:[0,1]
	v_mov_b32_e32 v113, v108
	v_pk_add_f32 v[108:109], v[114:115], v[112:113] neg_lo:[0,1] neg_hi:[0,1]
	v_add_f32_e32 v2, 1.0, v2
	v_add_f32_e32 v106, v106, v109
	v_add_f32_e32 v106, v108, v106
	v_add_f32_e32 v109, v120, v119
	v_add_f32_e32 v106, v111, v106
	v_sub_f32_e32 v108, v109, v120
	v_mul_f32_e32 v106, v118, v106
	v_sub_f32_e32 v108, v119, v108
	v_add_f32_e32 v106, v108, v106
	v_add_f32_e32 v110, v109, v106
	v_mul_f32_e32 v112, v110, v110
	v_fmamk_f32 v108, v112, 0x3e9b6dac, v211
	v_fmaak_f32 v153, v112, v108, 0x3f2aaada
	v_cvt_f32_i32_e32 v108, v116
	v_sub_f32_e32 v109, v110, v109
	v_sub_f32_e32 v106, v106, v109
	v_mul_f32_e32 v109, v110, v112
	v_pk_mul_f32 v[112:113], v[108:109], v[152:153]
	v_ldexp_f32 v111, v110, 1
	v_fma_f32 v110, v108, s3, -v112
	v_fmac_f32_e32 v110, 0xb102e308, v108
	v_pk_add_f32 v[108:109], v[112:113], v[110:111]
	v_ldexp_f32 v106, v106, 1
	v_sub_f32_e32 v111, v109, v111
	v_sub_f32_e32 v111, v113, v111
	v_add_f32_e32 v115, v106, v111
	v_mov_b32_e32 v114, v112
	v_pk_add_f32 v[112:113], v[108:109], v[112:113] neg_lo:[0,1] neg_hi:[0,1]
	v_pk_add_f32 v[116:117], v[108:109], v[114:115]
	v_mov_b32_e32 v111, v108
	v_mov_b32_e32 v113, v117
	v_pk_add_f32 v[118:119], v[110:111], v[112:113] neg_lo:[0,1] neg_hi:[0,1]
	v_pk_add_f32 v[110:111], v[110:111], v[112:113]
	v_mov_b32_e32 v114, v115
	v_pk_add_f32 v[112:113], v[110:111], v[108:109] op_sel:[1,0] op_sel_hi:[0,1] neg_lo:[0,1] neg_hi:[0,1]
	v_pk_add_f32 v[120:121], v[116:117], v[112:113] op_sel_hi:[1,0] neg_lo:[0,1] neg_hi:[0,1]
	v_mov_b32_e32 v116, v117
	v_mov_b32_e32 v117, v111
	v_pk_mov_b32 v[112:113], v[108:109], v[112:113] op_sel:[1,0]
	v_mov_b32_e32 v115, v108
	v_pk_add_f32 v[112:113], v[116:117], v[112:113] neg_lo:[0,1] neg_hi:[0,1]
	v_mov_b32_e32 v120, v118
	v_pk_add_f32 v[108:109], v[114:115], v[112:113] neg_lo:[0,1] neg_hi:[0,1]
	v_mov_b32_e32 v119, v111
	v_pk_add_f32 v[112:113], v[120:121], v[108:109]
	v_exp_f32_e32 v18, v18
	v_pk_add_f32 v[114:115], v[112:113], v[112:113] op_sel:[0,1] op_sel_hi:[1,0]
	v_lshl_add_u64 v[120:121], v[54:55], 0, v[80:81]
	v_pk_add_f32 v[110:111], v[110:111], v[114:115] op_sel:[1,0] op_sel_hi:[0,1]
	v_mov_b32_e32 v113, v110
	v_pk_add_f32 v[116:117], v[112:113], v[118:119] neg_lo:[0,1] neg_hi:[0,1]
	v_mov_b32_e32 v109, v114
	v_sub_f32_e32 v106, v112, v116
	v_pk_add_f32 v[108:109], v[108:109], v[116:117] neg_lo:[0,1] neg_hi:[0,1]
	v_sub_f32_e32 v106, v118, v106
	v_add_f32_e32 v106, v108, v106
	v_add_f32_e32 v106, v106, v109
	v_add_f32_e32 v106, v110, v106
	v_cndmask_b32_e64 v106, v217, v106, s[0:1]
	v_cmp_ngt_f32_e64 s[0:1], -1.0, v0
	v_add_f32_e32 v18, 1.0, v18
	v_rcp_f32_e32 v109, v18
	v_cndmask_b32_e64 v106, v218, v106, s[0:1]
	v_cmp_neq_f32_e64 s[0:1], -1.0, v0
	v_lshl_add_u64 v[80:81], v[56:57], 0, v[80:81]
	s_nop 0
	v_cndmask_b32_e64 v106, v219, v106, s[0:1]
	v_cmp_lt_f32_e64 s[0:1], |v0|, s21
	s_nop 1
	v_cndmask_b32_e64 v0, v106, v0, s[0:1]
	v_rcp_f32_e32 v106, v2
	ds_read_u16 v2, v41
	s_waitcnt lgkmcnt(0)
; DI float bf2f(u16 v) { return __uint_as_float(((unsigned)v) << 16); }
; DI int crow(int i, int h) { return (i & 3) + 8 * (i >> 2) + 4 * h; }
; DI void lru_item(const Params& p, int l, int b, int chunk, int blk, bool fin, char* smem, int tid) {
;     ...
;       for (int i = 0; i < 16; i++) {
;         const int tok = tb * 32 + crow(i, h);
;         const float rr = __builtin_amdgcn_rcpf(1.f + __expf(-(ga[i] + b_a))), ii = __builtin_amdgcn_rcpf(1.f + __expf(-(gx[i] + b_x)));
;         const float la = -8.f * rr * sp;
;         const float a = __expf(la);
;         const float x2 = 2.f * la;
;         const float ser = -x2 * (1.f + x2 * (0.5f + x2 * (0.16666667f + x2 * (0.041666668f + x2 * 0.0083333338f))));
;         const float om = (x2 > -0.25f) ? ser : (1.f - a * a);
;         const float u = __builtin_amdgcn_sqrtf(fmaxf(om, 0.f)) * ii * bf2f(xcb[tok][chn]);
;         au[(dir * 64 + tok) * 64 + chn] = make_float2(a, u);
;       }
	v_lshlrev_b32_e32 v110, 16, v2
	v_add_f32_e32 v2, v19, v71
	v_mul_f32_e32 v2, 0xbfb8aa3b, v2
	v_exp_f32_e32 v2, v2
	s_nop 0
	v_add_f32_e32 v2, 1.0, v2
	v_rcp_f32_e32 v108, v2
	v_add_f32_e32 v2, v3, v107
	v_mul_f32_e32 v2, 0xbfb8aa3b, v2
	v_exp_f32_e32 v2, v2
	s_nop 0
	v_add_f32_e32 v2, 1.0, v2
	v_rcp_f32_e32 v111, v2
	v_pk_mul_f32 v[2:3], v[108:109], s[24:25] op_sel_hi:[1,0]
	s_nop 0
	v_pk_mul_f32 v[2:3], v[2:3], v[0:1] op_sel_hi:[1,0]
	s_nop 0
	v_mul_f32_e32 v18, 0x3fb8aa3b, v3
	v_pk_add_f32 v[108:109], v[2:3], v[2:3]
	v_exp_f32_e32 v18, v18
	v_fmamk_f32 v3, v109, 0x3c088889, v212
	v_fmaak_f32 v3, v109, v3, 0x3e2aaaab
	v_fma_f32 v3, v109, v3, 0.5
	v_fma_f32 v3, v109, v3, 1.0
	v_mul_f32_e64 v3, v3, -v109
	v_fma_f32 v19, -v18, v18, 1.0
	v_cmp_lt_f32_e64 s[12:13], s22, v109
	v_mul_f32_e32 v2, 0x3fb8aa3b, v2
	v_exp_f32_e32 v2, v2
	v_cndmask_b32_e64 v3, v19, v3, s[12:13]
	v_max_f32_e32 v3, 0, v3
	v_sqrt_f32_e32 v3, v3
	v_cmp_lt_f32_e64 s[0:1], s22, v108
	v_mul_f32_e32 v3, v106, v3
	v_mul_f32_e32 v19, v3, v110
	v_fmamk_f32 v3, v108, 0x3c088889, v212
	v_fmaak_f32 v3, v108, v3, 0x3e2aaaab
	v_fma_f32 v3, v108, v3, 0.5
	v_add_u32_e32 v106, v40, v88
	v_fma_f32 v3, v108, v3, 1.0
	ds_write_b64 v106, v[18:19] offset:9216
	v_mul_f32_e64 v3, v3, -v108
	v_fma_f32 v18, -v2, v2, 1.0
	v_cndmask_b32_e64 v3, v18, v3, s[0:1]
	v_max_f32_e32 v3, 0, v3
	ds_read_u16 v18, v41 offset:144
	v_sqrt_f32_e32 v3, v3
	s_waitcnt lgkmcnt(0)
	v_lshlrev_b32_e32 v18, 16, v18
	v_mul_f32_e32 v3, v111, v3
	v_mul_f32_e32 v3, v3, v18
	ds_write_b64 v39, v[2:3] offset:9216
	v_add_f32_e32 v2, v20, v71
	v_mul_f32_e32 v2, 0xbfb8aa3b, v2
	v_exp_f32_e32 v2, v2
	s_nop 0
	v_add_f32_e32 v2, 1.0, v2
	v_rcp_f32_e32 v3, v2
	v_add_f32_e32 v2, v4, v107
	v_mul_f32_e32 v2, 0xbfb8aa3b, v2
	v_exp_f32_e32 v2, v2
	v_add_f32_e32 v4, v5, v107
	v_mul_f32_e32 v4, 0xbfb8aa3b, v4
	v_exp_f32_e32 v4, v4
	v_add_f32_e32 v2, 1.0, v2
	v_rcp_f32_e32 v20, v2
	ds_read_u16 v2, v41 offset:288
	v_add_f32_e32 v4, 1.0, v4
	s_waitcnt lgkmcnt(0)
	v_lshlrev_b32_e32 v108, 16, v2
	v_add_f32_e32 v2, v21, v71
	v_mul_f32_e32 v2, 0xbfb8aa3b, v2
	v_exp_f32_e32 v2, v2
	v_rcp_f32_e32 v21, v4
	v_add_f32_e32 v2, 1.0, v2
	v_rcp_f32_e32 v2, v2
	s_nop 0
	v_pk_mul_f32 v[2:3], v[2:3], s[24:25] op_sel_hi:[1,0]
	s_nop 0
	v_pk_mul_f32 v[2:3], v[2:3], v[0:1] op_sel_hi:[1,0]
	s_nop 0
	v_mul_f32_e32 v4, 0x3fb8aa3b, v3
	v_pk_add_f32 v[18:19], v[2:3], v[2:3]
	v_exp_f32_e32 v4, v4
	v_fmamk_f32 v3, v19, 0x3c088889, v212
	v_fmaak_f32 v3, v19, v3, 0x3e2aaaab
	v_fma_f32 v3, v19, v3, 0.5
	v_fma_f32 v3, v19, v3, 1.0
	v_mul_f32_e64 v3, v3, -v19
	v_fma_f32 v5, -v4, v4, 1.0
	v_cmp_lt_f32_e64 s[12:13], s22, v19
	v_mul_f32_e32 v2, 0x3fb8aa3b, v2
	v_exp_f32_e32 v2, v2
	v_cndmask_b32_e64 v3, v5, v3, s[12:13]
	v_max_f32_e32 v3, 0, v3
	v_sqrt_f32_e32 v3, v3
	v_cmp_lt_f32_e64 s[0:1], s22, v18
	v_mul_f32_e32 v3, v20, v3
	v_mul_f32_e32 v5, v3, v108
	v_fmamk_f32 v3, v18, 0x3c088889, v212
	v_fmaak_f32 v3, v18, v3, 0x3e2aaaab
	v_fma_f32 v3, v18, v3, 0.5
	v_fma_f32 v3, v18, v3, 1.0
	ds_write_b64 v43, v[4:5] offset:9216
	v_mul_f32_e64 v3, v3, -v18
	v_fma_f32 v4, -v2, v2, 1.0
	v_cndmask_b32_e64 v3, v4, v3, s[0:1]
	v_max_f32_e32 v3, 0, v3
	ds_read_u16 v4, v41 offset:432
	v_sqrt_f32_e32 v3, v3
	s_waitcnt lgkmcnt(0)
	v_lshlrev_b32_e32 v4, 16, v4
	v_mul_f32_e32 v3, v21, v3
	v_mul_f32_e32 v3, v3, v4
	ds_write_b64 v61, v[2:3] offset:9216
	v_add_f32_e32 v2, v22, v71
	v_mul_f32_e32 v2, 0xbfb8aa3b, v2
	v_exp_f32_e32 v2, v2
	v_add_f32_e32 v4, v7, v107
	v_mul_f32_e32 v4, 0xbfb8aa3b, v4
	v_exp_f32_e32 v4, v4
	v_add_f32_e32 v2, 1.0, v2
	v_rcp_f32_e32 v3, v2
	v_add_f32_e32 v2, v6, v107
	v_mul_f32_e32 v2, 0xbfb8aa3b, v2
	v_exp_f32_e32 v2, v2
	v_add_f32_e32 v4, 1.0, v4
	v_rcp_f32_e32 v19, v4
	v_add_f32_e32 v2, 1.0, v2
	v_rcp_f32_e32 v5, v2
	ds_read_u16 v2, v41 offset:1152
	s_waitcnt lgkmcnt(0)
	v_lshlrev_b32_e32 v18, 16, v2
	v_add_f32_e32 v2, v23, v71
	v_mul_f32_e32 v2, 0xbfb8aa3b, v2
	v_exp_f32_e32 v2, v2
	s_nop 0
	v_add_f32_e32 v2, 1.0, v2
	v_rcp_f32_e32 v2, v2
	s_nop 0
	v_pk_mul_f32 v[2:3], v[2:3], s[24:25] op_sel_hi:[1,0]
	s_nop 0
	v_pk_mul_f32 v[2:3], v[2:3], v[0:1] op_sel_hi:[1,0]
	s_nop 0
	v_mul_f32_e32 v4, 0x3fb8aa3b, v3
	v_pk_add_f32 v[6:7], v[2:3], v[2:3]
	v_exp_f32_e32 v4, v4
	v_fmamk_f32 v3, v7, 0x3c088889, v212
	v_fmaak_f32 v3, v7, v3, 0x3e2aaaab
	v_fma_f32 v3, v7, v3, 0.5
	v_fma_f32 v3, v7, v3, 1.0
	v_mul_f32_e64 v3, v3, -v7
	v_fma_f32 v20, -v4, v4, 1.0
	v_cmp_lt_f32_e64 s[12:13], s22, v7
	v_mul_f32_e32 v2, 0x3fb8aa3b, v2
	v_exp_f32_e32 v2, v2
	v_cndmask_b32_e64 v3, v20, v3, s[12:13]
	v_max_f32_e32 v3, 0, v3
	v_sqrt_f32_e32 v3, v3
	v_cmp_lt_f32_e64 s[0:1], s22, v6
	v_mul_f32_e32 v3, v5, v3
	v_mul_f32_e32 v5, v3, v18
	v_fmamk_f32 v3, v6, 0x3c088889, v212
	v_fmaak_f32 v3, v6, v3, 0x3e2aaaab
	v_fma_f32 v3, v6, v3, 0.5
	v_fma_f32 v3, v6, v3, 1.0
	ds_write_b64 v94, v[4:5] offset:9216
	v_mul_f32_e64 v3, v3, -v6
	v_fma_f32 v4, -v2, v2, 1.0
	v_cndmask_b32_e64 v3, v4, v3, s[0:1]
	v_max_f32_e32 v3, 0, v3
	ds_read_u16 v4, v41 offset:1296
	v_sqrt_f32_e32 v3, v3
	s_waitcnt lgkmcnt(0)
	v_lshlrev_b32_e32 v4, 16, v4
	v_mul_f32_e32 v3, v19, v3
	v_mul_f32_e32 v3, v3, v4
	ds_write_b64 v95, v[2:3] offset:9216
	v_add_f32_e32 v2, v24, v71
	v_mul_f32_e32 v2, 0xbfb8aa3b, v2
	v_exp_f32_e32 v2, v2
	v_add_f32_e32 v4, v9, v107
	v_mul_f32_e32 v4, 0xbfb8aa3b, v4
	v_exp_f32_e32 v4, v4
	v_add_f32_e32 v2, 1.0, v2
	v_rcp_f32_e32 v3, v2
	v_add_f32_e32 v2, v8, v107
	v_mul_f32_e32 v2, 0xbfb8aa3b, v2
	v_exp_f32_e32 v2, v2
	v_add_f32_e32 v4, 1.0, v4
	v_rcp_f32_e32 v9, v4
	v_add_f32_e32 v2, 1.0, v2
	v_rcp_f32_e32 v5, v2
	ds_read_u16 v2, v41 offset:1440
	s_waitcnt lgkmcnt(0)
; DI float bf2f(u16 v) { return __uint_as_float(((unsigned)v) << 16); }
; DI int crow(int i, int h) { return (i & 3) + 8 * (i >> 2) + 4 * h; }
; DI void lru_item(const Params& p, int l, int b, int chunk, int blk, bool fin, char* smem, int tid) {
;     ...
;       for (int i = 0; i < 16; i++) {
;         const int tok = tb * 32 + crow(i, h);
;         const float rr = __builtin_amdgcn_rcpf(1.f + __expf(-(ga[i] + b_a))), ii = __builtin_amdgcn_rcpf(1.f + __expf(-(gx[i] + b_x)));
;         const float la = -8.f * rr * sp;
;         const float a = __expf(la);
;         const float x2 = 2.f * la;
;         const float ser = -x2 * (1.f + x2 * (0.5f + x2 * (0.16666667f + x2 * (0.041666668f + x2 * 0.0083333338f))));
;         const float om = (x2 > -0.25f) ? ser : (1.f - a * a);
;         const float u = __builtin_amdgcn_sqrtf(fmaxf(om, 0.f)) * ii * bf2f(xcb[tok][chn]);
;         au[(dir * 64 + tok) * 64 + chn] = make_float2(a, u);
;       }
	v_lshlrev_b32_e32 v8, 16, v2
	v_add_f32_e32 v2, v25, v71
	v_mul_f32_e32 v2, 0xbfb8aa3b, v2
	v_exp_f32_e32 v2, v2
	s_nop 0
	v_add_f32_e32 v2, 1.0, v2
	v_rcp_f32_e32 v2, v2
	s_nop 0
	v_pk_mul_f32 v[2:3], v[2:3], s[24:25] op_sel_hi:[1,0]
	s_nop 0
	v_pk_mul_f32 v[2:3], v[2:3], v[0:1] op_sel_hi:[1,0]
	s_nop 0
	v_mul_f32_e32 v4, 0x3fb8aa3b, v3
	v_pk_add_f32 v[6:7], v[2:3], v[2:3]
	v_exp_f32_e32 v4, v4
	v_fmamk_f32 v3, v7, 0x3c088889, v212
	v_fmaak_f32 v3, v7, v3, 0x3e2aaaab
	v_fma_f32 v3, v7, v3, 0.5
	v_fma_f32 v3, v7, v3, 1.0
	v_mul_f32_e64 v3, v3, -v7
	v_fma_f32 v18, -v4, v4, 1.0
	v_cmp_lt_f32_e64 s[12:13], s22, v7
	v_mul_f32_e32 v2, 0x3fb8aa3b, v2
	v_exp_f32_e32 v2, v2
	v_cndmask_b32_e64 v3, v18, v3, s[12:13]
	v_max_f32_e32 v3, 0, v3
	v_sqrt_f32_e32 v3, v3
	v_cmp_lt_f32_e64 s[0:1], s22, v6
	v_mul_f32_e32 v3, v5, v3
	v_mul_f32_e32 v5, v3, v8
	v_fmamk_f32 v3, v6, 0x3c088889, v212
	v_fmaak_f32 v3, v6, v3, 0x3e2aaaab
	v_fma_f32 v3, v6, v3, 0.5
	v_fma_f32 v3, v6, v3, 1.0
	ds_write_b64 v96, v[4:5] offset:9216
	v_mul_f32_e64 v3, v3, -v6
	v_fma_f32 v4, -v2, v2, 1.0
	v_cndmask_b32_e64 v3, v4, v3, s[0:1]
	v_max_f32_e32 v3, 0, v3
	ds_read_u16 v4, v41 offset:1584
	v_sqrt_f32_e32 v3, v3
	s_waitcnt lgkmcnt(0)
	v_lshlrev_b32_e32 v4, 16, v4
	v_mul_f32_e32 v3, v9, v3
	v_mul_f32_e32 v3, v3, v4
	ds_write_b64 v97, v[2:3] offset:9216
	v_add_f32_e32 v2, v26, v71
	v_mul_f32_e32 v2, 0xbfb8aa3b, v2
	v_exp_f32_e32 v2, v2
	v_add_f32_e32 v4, v11, v107
	v_mul_f32_e32 v4, 0xbfb8aa3b, v4
	v_exp_f32_e32 v4, v4
	v_add_f32_e32 v2, 1.0, v2
	v_rcp_f32_e32 v3, v2
	v_add_f32_e32 v2, v10, v107
	v_mul_f32_e32 v2, 0xbfb8aa3b, v2
	v_exp_f32_e32 v2, v2
	v_add_f32_e32 v4, 1.0, v4
	v_rcp_f32_e32 v9, v4
	v_add_f32_e32 v2, 1.0, v2
	v_rcp_f32_e32 v5, v2
	ds_read_u16 v2, v41 offset:2304
	s_waitcnt lgkmcnt(0)
	v_lshlrev_b32_e32 v8, 16, v2
	v_add_f32_e32 v2, v27, v71
	v_mul_f32_e32 v2, 0xbfb8aa3b, v2
	v_exp_f32_e32 v2, v2
	s_nop 0
	v_add_f32_e32 v2, 1.0, v2
	v_rcp_f32_e32 v2, v2
	s_nop 0
	v_pk_mul_f32 v[2:3], v[2:3], s[24:25] op_sel_hi:[1,0]
	s_nop 0
	v_pk_mul_f32 v[2:3], v[2:3], v[0:1] op_sel_hi:[1,0]
	s_nop 0
	v_mul_f32_e32 v4, 0x3fb8aa3b, v3
	v_pk_add_f32 v[6:7], v[2:3], v[2:3]
	v_exp_f32_e32 v4, v4
	v_fmamk_f32 v3, v7, 0x3c088889, v212
	v_fmaak_f32 v3, v7, v3, 0x3e2aaaab
	v_fma_f32 v3, v7, v3, 0.5
	v_fma_f32 v3, v7, v3, 1.0
	v_mul_f32_e64 v3, v3, -v7
	v_fma_f32 v10, -v4, v4, 1.0
	v_cmp_lt_f32_e64 s[12:13], s22, v7
	v_mul_f32_e32 v2, 0x3fb8aa3b, v2
	v_exp_f32_e32 v2, v2
	v_cndmask_b32_e64 v3, v10, v3, s[12:13]
	v_max_f32_e32 v3, 0, v3
	v_sqrt_f32_e32 v3, v3
	v_cmp_lt_f32_e64 s[0:1], s22, v6
	v_mul_f32_e32 v3, v5, v3
	v_mul_f32_e32 v5, v3, v8
	v_fmamk_f32 v3, v6, 0x3c088889, v212
	v_fmaak_f32 v3, v6, v3, 0x3e2aaaab
	v_fma_f32 v3, v6, v3, 0.5
	v_fma_f32 v3, v6, v3, 1.0
	ds_write_b64 v98, v[4:5] offset:9216
	v_mul_f32_e64 v3, v3, -v6
	v_fma_f32 v4, -v2, v2, 1.0
	v_cndmask_b32_e64 v3, v4, v3, s[0:1]
	v_max_f32_e32 v3, 0, v3
	ds_read_u16 v4, v41 offset:2448
	v_sqrt_f32_e32 v3, v3
	s_waitcnt lgkmcnt(0)
	v_lshlrev_b32_e32 v4, 16, v4
	v_mul_f32_e32 v3, v9, v3
	v_mul_f32_e32 v3, v3, v4
	ds_write_b64 v99, v[2:3] offset:9216
	v_add_f32_e32 v2, v28, v71
	v_mul_f32_e32 v2, 0xbfb8aa3b, v2
	v_exp_f32_e32 v2, v2
	v_add_f32_e32 v4, v13, v107
	v_mul_f32_e32 v4, 0xbfb8aa3b, v4
	v_exp_f32_e32 v4, v4
	v_add_f32_e32 v2, 1.0, v2
	v_rcp_f32_e32 v3, v2
	v_add_f32_e32 v2, v12, v107
	v_mul_f32_e32 v2, 0xbfb8aa3b, v2
	v_exp_f32_e32 v2, v2
	v_add_f32_e32 v4, 1.0, v4
	v_rcp_f32_e32 v9, v4
	v_add_f32_e32 v2, 1.0, v2
	v_rcp_f32_e32 v5, v2
	ds_read_u16 v2, v41 offset:2592
	s_waitcnt lgkmcnt(0)
	v_lshlrev_b32_e32 v8, 16, v2
	v_add_f32_e32 v2, v29, v71
	v_mul_f32_e32 v2, 0xbfb8aa3b, v2
	v_exp_f32_e32 v2, v2
	s_nop 0
	v_add_f32_e32 v2, 1.0, v2
	v_rcp_f32_e32 v2, v2
	s_nop 0
	v_pk_mul_f32 v[2:3], v[2:3], s[24:25] op_sel_hi:[1,0]
	s_nop 0
	v_pk_mul_f32 v[2:3], v[2:3], v[0:1] op_sel_hi:[1,0]
	s_nop 0
	v_mul_f32_e32 v4, 0x3fb8aa3b, v3
	v_pk_add_f32 v[6:7], v[2:3], v[2:3]
	v_exp_f32_e32 v4, v4
	v_fmamk_f32 v3, v7, 0x3c088889, v212
	v_fmaak_f32 v3, v7, v3, 0x3e2aaaab
	v_fma_f32 v3, v7, v3, 0.5
	v_fma_f32 v3, v7, v3, 1.0
	v_mul_f32_e64 v3, v3, -v7
	v_fma_f32 v10, -v4, v4, 1.0
	v_cmp_lt_f32_e64 s[12:13], s22, v7
	v_mul_f32_e32 v2, 0x3fb8aa3b, v2
	v_exp_f32_e32 v2, v2
	v_cndmask_b32_e64 v3, v10, v3, s[12:13]
	v_max_f32_e32 v3, 0, v3
	v_sqrt_f32_e32 v3, v3
	v_cmp_lt_f32_e64 s[0:1], s22, v6
	v_mul_f32_e32 v3, v5, v3
	v_mul_f32_e32 v5, v3, v8
	v_fmamk_f32 v3, v6, 0x3c088889, v212
	v_fmaak_f32 v3, v6, v3, 0x3e2aaaab
	v_fma_f32 v3, v6, v3, 0.5
	v_fma_f32 v3, v6, v3, 1.0
	ds_write_b64 v100, v[4:5] offset:9216
	v_mul_f32_e64 v3, v3, -v6
	v_fma_f32 v4, -v2, v2, 1.0
	v_cndmask_b32_e64 v3, v4, v3, s[0:1]
	v_max_f32_e32 v3, 0, v3
	ds_read_u16 v4, v41 offset:2736
	v_sqrt_f32_e32 v3, v3
	s_waitcnt lgkmcnt(0)
	v_lshlrev_b32_e32 v4, 16, v4
	v_mul_f32_e32 v3, v9, v3
	v_mul_f32_e32 v3, v3, v4
	ds_write_b64 v101, v[2:3] offset:9216
	v_add_f32_e32 v2, v30, v71
	v_mul_f32_e32 v2, 0xbfb8aa3b, v2
	v_exp_f32_e32 v2, v2
	v_add_f32_e32 v4, v15, v107
	v_mul_f32_e32 v4, 0xbfb8aa3b, v4
	v_exp_f32_e32 v4, v4
	v_add_f32_e32 v2, 1.0, v2
	v_rcp_f32_e32 v3, v2
	v_add_f32_e32 v2, v14, v107
	v_mul_f32_e32 v2, 0xbfb8aa3b, v2
	v_exp_f32_e32 v2, v2
	v_add_f32_e32 v4, 1.0, v4
	v_rcp_f32_e32 v9, v4
	v_add_f32_e32 v2, 1.0, v2
	v_rcp_f32_e32 v5, v2
	ds_read_u16 v2, v41 offset:3456
	s_waitcnt lgkmcnt(0)
; #define MFMA(a, b, c) __builtin_amdgcn_mfma_f32_32x32x16_bf16((a), (b), (c), 0, 0, 0)
; DI void lru_item(const Params& p, int l, int b, int chunk, int blk, bool fin, char* smem, int tid) {
;     ...
;     for (int dir = 0; dir < 2; dir++) {
;       f32x16 ga, gx;
; #pragma unroll
;       for (int i = 0; i < 16; i++) { ga[i] = 0.f; gx[i] = 0.f; }
;       const u16* wa = p.WtA + (((size_t)l * 2 + dir) * 4 + blk) * 4096 + (size_t)chn * 64 + h * 8;
;       const u16* wx = p.WtX + (((size_t)l * 2 + dir) * 4 + blk) * 4096 + (size_t)chn * 64 + h * 8;
; #pragma unroll
;       for (int ks = 0; ks < 4; ks++) {
;         bf16x8 a = *(const bf16x8*)&xcb[tb * 32 + r][ks * 16 + h * 8];
;         bf16x8 ba = *(const bf16x8*)(wa + ks * 16), bx = *(const bf16x8*)(wx + ks * 16);
;         ga = MFMA(a, ba, ga); gx = MFMA(a, bx, gx);
;       }
;       const int pi = (l * 2 + dir) * 256 + c0 + chn;
;       const float b_a = p.ba[pi], b_x = p.bx[pi], lam = p.lam[pi];
	v_lshlrev_b32_e32 v8, 16, v2
	v_add_f32_e32 v2, v31, v71
	v_mul_f32_e32 v2, 0xbfb8aa3b, v2
	v_exp_f32_e32 v2, v2
	s_nop 0
	v_add_f32_e32 v2, 1.0, v2
	v_rcp_f32_e32 v2, v2
	s_nop 0
	v_pk_mul_f32 v[2:3], v[2:3], s[24:25] op_sel_hi:[1,0]
	s_nop 0
	v_pk_mul_f32 v[2:3], v[2:3], v[0:1] op_sel_hi:[1,0]
	s_nop 0
	v_mul_f32_e32 v4, 0x3fb8aa3b, v3
	v_pk_add_f32 v[6:7], v[2:3], v[2:3]
	v_exp_f32_e32 v4, v4
	v_fmamk_f32 v3, v7, 0x3c088889, v212
	v_fmaak_f32 v3, v7, v3, 0x3e2aaaab
	v_fma_f32 v3, v7, v3, 0.5
	v_fma_f32 v3, v7, v3, 1.0
	v_mul_f32_e64 v3, v3, -v7
	v_fma_f32 v10, -v4, v4, 1.0
	v_cmp_lt_f32_e64 s[12:13], s22, v7
	v_mul_f32_e32 v2, 0x3fb8aa3b, v2
	v_exp_f32_e32 v2, v2
	v_cndmask_b32_e64 v3, v10, v3, s[12:13]
	v_max_f32_e32 v3, 0, v3
	v_sqrt_f32_e32 v3, v3
	v_cmp_lt_f32_e64 s[0:1], s22, v6
	v_mul_f32_e32 v3, v5, v3
	v_mul_f32_e32 v5, v3, v8
	v_fmamk_f32 v3, v6, 0x3c088889, v212
	v_fmaak_f32 v3, v6, v3, 0x3e2aaaab
	v_fma_f32 v3, v6, v3, 0.5
	v_fma_f32 v3, v6, v3, 1.0
	ds_write_b64 v102, v[4:5] offset:9216
	v_mul_f32_e64 v3, v3, -v6
	v_fma_f32 v4, -v2, v2, 1.0
	v_cndmask_b32_e64 v3, v4, v3, s[0:1]
	v_max_f32_e32 v3, 0, v3
	ds_read_u16 v4, v41 offset:3600
	v_sqrt_f32_e32 v3, v3
	s_waitcnt lgkmcnt(0)
	v_lshlrev_b32_e32 v4, 16, v4
	v_mul_f32_e32 v3, v9, v3
	v_mul_f32_e32 v3, v3, v4
	ds_write_b64 v103, v[2:3] offset:9216
	v_add_f32_e32 v2, v32, v71
	v_mul_f32_e32 v2, 0xbfb8aa3b, v2
	v_exp_f32_e32 v2, v2
	v_add_f32_e32 v4, v17, v107
	v_mul_f32_e32 v4, 0xbfb8aa3b, v4
	v_exp_f32_e32 v4, v4
	v_add_f32_e32 v2, 1.0, v2
	v_rcp_f32_e32 v3, v2
	v_add_f32_e32 v2, v16, v107
	v_mul_f32_e32 v2, 0xbfb8aa3b, v2
	v_exp_f32_e32 v2, v2
	v_add_f32_e32 v4, 1.0, v4
	v_rcp_f32_e32 v9, v4
	v_add_f32_e32 v2, 1.0, v2
	v_rcp_f32_e32 v5, v2
	ds_read_u16 v2, v41 offset:3744
	s_waitcnt lgkmcnt(0)
	v_lshlrev_b32_e32 v8, 16, v2
	v_add_f32_e32 v2, v33, v71
	v_mul_f32_e32 v2, 0xbfb8aa3b, v2
	v_exp_f32_e32 v2, v2
	s_nop 0
	v_add_f32_e32 v2, 1.0, v2
	v_rcp_f32_e32 v2, v2
	s_nop 0
	v_pk_mul_f32 v[2:3], v[2:3], s[24:25] op_sel_hi:[1,0]
	s_nop 0
	v_pk_mul_f32 v[2:3], v[2:3], v[0:1] op_sel_hi:[1,0]
	s_nop 0
	v_mul_f32_e32 v0, 0x3fb8aa3b, v3
	v_pk_add_f32 v[6:7], v[2:3], v[2:3]
	v_exp_f32_e32 v4, v0
	v_fmamk_f32 v0, v7, 0x3c088889, v212
	v_fmaak_f32 v0, v7, v0, 0x3e2aaaab
	v_fma_f32 v0, v7, v0, 0.5
	v_fma_f32 v0, v7, v0, 1.0
	v_mul_f32_e64 v0, v0, -v7
	v_fma_f32 v3, -v4, v4, 1.0
	v_cmp_lt_f32_e64 s[12:13], s22, v7
	v_cmp_lt_f32_e64 s[0:1], s22, v6
	s_nop 0
	v_cndmask_b32_e64 v0, v3, v0, s[12:13]
	v_max_f32_e32 v0, 0, v0
	v_sqrt_f32_e32 v0, v0
	s_nop 0
	v_mul_f32_e32 v0, v5, v0
	v_mul_f32_e32 v5, v0, v8
	v_mul_f32_e32 v0, 0x3fb8aa3b, v2
	v_exp_f32_e32 v2, v0
	v_fmamk_f32 v0, v6, 0x3c088889, v212
	v_fmaak_f32 v0, v6, v0, 0x3e2aaaab
	v_fma_f32 v0, v6, v0, 0.5
	v_fma_f32 v0, v6, v0, 1.0
	v_mul_f32_e64 v0, v0, -v6
	v_fma_f32 v3, -v2, v2, 1.0
	ds_write_b64 v104, v[4:5] offset:9216
	v_cndmask_b32_e64 v0, v3, v0, s[0:1]
	v_max_f32_e32 v0, 0, v0
	ds_read_u16 v3, v41 offset:3888
	v_sqrt_f32_e32 v0, v0
	s_waitcnt lgkmcnt(0)
	v_lshlrev_b32_e32 v3, 16, v3
	v_mul_f32_e32 v0, v9, v0
	v_mul_f32_e32 v3, v0, v3
	ds_write_b64 v105, v[2:3] offset:9216
	global_load_dwordx4 v[2:5], v[120:121], off
	global_load_dwordx4 v[6:9], v[80:81], off
	ds_read_b128 v[10:13], v87
	ds_read_b128 v[108:111], v87 offset:32
	global_load_dwordx4 v[112:115], v[120:121], off offset:32
	global_load_dwordx4 v[116:119], v[80:81], off offset:32
	s_waitcnt vmcnt(3) lgkmcnt(1)
	v_mfma_f32_32x32x16_bf16 v[18:33], v[10:13], v[2:5], 0
	s_waitcnt vmcnt(2)
	v_mfma_f32_32x32x16_bf16 v[2:17], v[10:13], v[6:9], 0
	s_waitcnt vmcnt(1) lgkmcnt(0)
	v_mfma_f32_32x32x16_bf16 v[18:33], v[108:111], v[112:115], v[18:33]
	s_waitcnt vmcnt(0)
	v_mfma_f32_32x32x16_bf16 v[2:17], v[108:111], v[116:119], v[2:17]
	ds_read_b128 v[108:111], v87 offset:64
	global_load_dwordx4 v[112:115], v[120:121], off offset:64
	global_load_dwordx4 v[116:119], v[80:81], off offset:64
	s_waitcnt vmcnt(1) lgkmcnt(0)
	v_mfma_f32_32x32x16_bf16 v[18:33], v[108:111], v[112:115], v[18:33]
	s_waitcnt vmcnt(0)
	v_mfma_f32_32x32x16_bf16 v[2:17], v[108:111], v[116:119], v[2:17]
	ds_read_b128 v[108:111], v87 offset:96
	global_load_dwordx4 v[112:115], v[120:121], off offset:96
	global_load_dwordx4 v[116:119], v[80:81], off offset:96
	s_nop 0
	s_waitcnt vmcnt(0)
	v_mov_b32_e32 v80, v182
	v_mov_b32_e32 v71, v183
	v_mov_b32_e32 v0, v186
	v_mul_f32_e32 v0, 0xbfb8aa3b, v0
	v_exp_f32_e32 v0, v0
	s_waitcnt lgkmcnt(0)
; DI float bf2f(u16 v) { return __uint_as_float(((unsigned)v) << 16); }
; DI int crow(int i, int h) { return (i & 3) + 8 * (i >> 2) + 4 * h; }
; DI void lru_item(const Params& p, int l, int b, int chunk, int blk, bool fin, char* smem, int tid) {
;     ...
;       const float b_a = p.ba[pi], b_x = p.bx[pi], lam = p.lam[pi];
;       const float sp = log1pf(__expf(-lam));
; #pragma unroll
;       for (int i = 0; i < 16; i++) {
;         const int tok = tb * 32 + crow(i, h);
;         const float rr = __builtin_amdgcn_rcpf(1.f + __expf(-(ga[i] + b_a))), ii = __builtin_amdgcn_rcpf(1.f + __expf(-(gx[i] + b_x)));
;         const float la = -8.f * rr * sp;
;         const float a = __expf(la);
;         const float x2 = 2.f * la;
;         const float ser = -x2 * (1.f + x2 * (0.5f + x2 * (0.16666667f + x2 * (0.041666668f + x2 * 0.0083333338f))));
;         const float om = (x2 > -0.25f) ? ser : (1.f - a * a);
;         const float u = __builtin_amdgcn_sqrtf(fmaxf(om, 0.f)) * ii * bf2f(xcb[tok][chn]);
;         au[(dir * 64 + tok) * 64 + chn] = make_float2(a, u);
;       }
	v_mfma_f32_32x32x16_bf16 v[18:33], v[108:111], v[112:115], v[18:33]
	v_add_f32_e32 v81, 1.0, v0
	v_add_f32_e32 v78, -1.0, v81
	v_sub_f32_e32 v79, v78, v81
	v_add_f32_e32 v79, 1.0, v79
	v_sub_f32_e32 v78, v0, v78
	v_add_f32_e32 v82, v78, v79
	v_frexp_mant_f32_e32 v78, v81
	v_cmp_gt_f32_e64 s[0:1], s2, v78
	v_cvt_f64_f32_e32 v[78:79], v81
	v_frexp_exp_i32_f64_e32 v78, v[78:79]
	v_subbrev_co_u32_e64 v107, s[0:1], 0, v78, s[0:1]
	v_sub_u32_e32 v78, 0, v107
	v_ldexp_f32 v79, v81, v78
	v_add_f32_e32 v81, -1.0, v79
	v_add_f32_e32 v83, 1.0, v79
	v_ldexp_f32 v78, v82, v78
	v_add_f32_e32 v82, 1.0, v81
	v_add_f32_e32 v84, -1.0, v83
	v_sub_f32_e32 v82, v79, v82
	v_sub_f32_e32 v79, v79, v84
	v_add_f32_e32 v82, v78, v82
	v_add_f32_e32 v78, v78, v79
	v_mfma_f32_32x32x16_bf16 v[2:17], v[108:111], v[116:119], v[2:17]
	v_add_f32_e32 v110, v83, v78
	v_rcp_f32_e32 v112, v110
	v_sub_f32_e32 v79, v110, v83
	v_sub_f32_e32 v111, v78, v79
	v_add_f32_e32 v79, v81, v82
	v_sub_f32_e32 v78, v79, v81
	v_mul_f32_e32 v113, v79, v112
	v_sub_f32_e32 v81, v82, v78
	v_mul_f32_e32 v82, v110, v113
	v_fma_f32 v84, v113, v110, -v82
	v_fmac_f32_e32 v84, v113, v111
	v_add_f32_e32 v78, v82, v84
	v_sub_f32_e32 v83, v79, v78
	v_pk_add_f32 v[108:109], v[78:79], v[82:83] neg_lo:[0,1] neg_hi:[0,1]
	v_mov_b32_e32 v85, v78
	v_pk_add_f32 v[78:79], v[108:109], v[84:85] neg_lo:[0,1] neg_hi:[0,1]
	v_add_f32_e32 v2, v2, v71
	v_add_f32_e32 v79, v81, v79
	v_add_f32_e32 v78, v78, v79
	v_add_f32_e32 v79, v83, v78
	v_mul_f32_e32 v81, v112, v79
	v_mul_f32_e32 v82, v110, v81
	v_fma_f32 v84, v81, v110, -v82
	v_fmac_f32_e32 v84, v81, v111
	v_sub_f32_e32 v83, v83, v79
	v_add_f32_e32 v110, v78, v83
	v_add_f32_e32 v78, v82, v84
	v_sub_f32_e32 v83, v79, v78
	v_pk_add_f32 v[108:109], v[78:79], v[82:83] neg_lo:[0,1] neg_hi:[0,1]
	v_mov_b32_e32 v85, v78
	v_pk_add_f32 v[78:79], v[108:109], v[84:85] neg_lo:[0,1] neg_hi:[0,1]
	v_mul_f32_e32 v2, 0xbfb8aa3b, v2
	v_add_f32_e32 v79, v110, v79
	v_add_f32_e32 v78, v78, v79
	v_add_f32_e32 v79, v113, v81
	v_add_f32_e32 v78, v83, v78
	v_sub_f32_e32 v82, v79, v113
	v_mul_f32_e32 v78, v112, v78
	v_sub_f32_e32 v81, v81, v82
	v_add_f32_e32 v81, v81, v78
	v_add_f32_e32 v82, v79, v81
	v_mul_f32_e32 v84, v82, v82
	v_fmamk_f32 v78, v84, 0x3e9b6dac, v211
	v_fmaak_f32 v153, v84, v78, 0x3f2aaada
	v_cvt_f32_i32_e32 v78, v107
	v_sub_f32_e32 v79, v82, v79
	v_sub_f32_e32 v79, v81, v79
	v_ldexp_f32 v81, v79, 1
	v_mul_f32_e32 v79, v82, v84
	v_pk_mul_f32 v[84:85], v[78:79], v[152:153]
	v_ldexp_f32 v83, v82, 1
	v_fma_f32 v82, v78, s3, -v84
	v_fmac_f32_e32 v82, 0xb102e308, v78
	v_pk_add_f32 v[78:79], v[84:85], v[82:83]
	v_mov_b32_e32 v108, v84
	v_sub_f32_e32 v83, v79, v83
	v_sub_f32_e32 v83, v85, v83
	v_add_f32_e32 v109, v81, v83
	v_pk_add_f32 v[84:85], v[78:79], v[84:85] neg_lo:[0,1] neg_hi:[0,1]
	v_pk_add_f32 v[110:111], v[78:79], v[108:109]
	v_mov_b32_e32 v83, v78
	v_mov_b32_e32 v85, v111
	v_pk_add_f32 v[112:113], v[82:83], v[84:85] neg_lo:[0,1] neg_hi:[0,1]
	v_pk_add_f32 v[82:83], v[82:83], v[84:85]
	v_mov_b32_e32 v108, v109
	v_pk_add_f32 v[84:85], v[82:83], v[78:79] op_sel:[1,0] op_sel_hi:[0,1] neg_lo:[0,1] neg_hi:[0,1]
	v_pk_add_f32 v[114:115], v[110:111], v[84:85] op_sel_hi:[1,0] neg_lo:[0,1] neg_hi:[0,1]
	v_mov_b32_e32 v110, v111
	v_mov_b32_e32 v111, v83
	v_pk_mov_b32 v[84:85], v[78:79], v[84:85] op_sel:[1,0]
	v_mov_b32_e32 v109, v78
	v_pk_add_f32 v[84:85], v[110:111], v[84:85] neg_lo:[0,1] neg_hi:[0,1]
	v_mov_b32_e32 v114, v112
	v_pk_add_f32 v[78:79], v[108:109], v[84:85] neg_lo:[0,1] neg_hi:[0,1]
	v_mov_b32_e32 v113, v83
	v_pk_add_f32 v[84:85], v[114:115], v[78:79]
	v_exp_f32_e32 v2, v2
	v_pk_add_f32 v[108:109], v[84:85], v[84:85] op_sel:[0,1] op_sel_hi:[1,0]
	v_cmp_neq_f32_e64 s[0:1], s20, v0
	v_pk_add_f32 v[82:83], v[82:83], v[108:109] op_sel:[1,0] op_sel_hi:[0,1]
	v_mov_b32_e32 v85, v82
	v_pk_add_f32 v[110:111], v[84:85], v[112:113] neg_lo:[0,1] neg_hi:[0,1]
	v_mov_b32_e32 v79, v108
	v_sub_f32_e32 v81, v84, v110
	v_pk_add_f32 v[78:79], v[78:79], v[110:111] neg_lo:[0,1] neg_hi:[0,1]
	v_sub_f32_e32 v81, v112, v81
	v_add_f32_e32 v2, 1.0, v2
	v_add_f32_e32 v78, v78, v81
	v_rcp_f32_e32 v81, v2
	ds_read_u16 v2, v41
	v_add_f32_e32 v78, v78, v79
	v_add_f32_e32 v78, v82, v78
	v_add_f32_e32 v18, v18, v80
	v_cndmask_b32_e64 v78, v217, v78, s[0:1]
	s_waitcnt lgkmcnt(0)
	v_lshlrev_b32_e32 v82, 16, v2
	v_add_f32_e32 v2, v19, v80
	v_mul_f32_e32 v2, 0xbfb8aa3b, v2
	v_exp_f32_e32 v2, v2
	v_cmp_ngt_f32_e64 s[0:1], -1.0, v0
	v_mul_f32_e32 v18, 0xbfb8aa3b, v18
	v_exp_f32_e32 v18, v18
	v_cndmask_b32_e64 v78, v218, v78, s[0:1]
	v_cmp_neq_f32_e64 s[0:1], -1.0, v0
	v_add_f32_e32 v2, 1.0, v2
	v_add_f32_e32 v18, 1.0, v18
	v_cndmask_b32_e64 v78, v219, v78, s[0:1]
	v_cmp_lt_f32_e64 s[0:1], |v0|, s21
	v_rcp_f32_e32 v79, v18
	s_nop 0
	v_cndmask_b32_e64 v0, v78, v0, s[0:1]
	v_rcp_f32_e32 v78, v2
	v_add_f32_e32 v2, v3, v71
	v_mul_f32_e32 v2, 0xbfb8aa3b, v2
	v_exp_f32_e32 v2, v2
	s_nop 0
	v_add_f32_e32 v2, 1.0, v2
	v_rcp_f32_e32 v83, v2
	v_pk_mul_f32 v[2:3], v[78:79], s[24:25] op_sel_hi:[1,0]
	s_nop 0
	v_pk_mul_f32 v[2:3], v[2:3], v[0:1] op_sel_hi:[1,0]
	s_nop 0
	v_mul_f32_e32 v18, 0x3fb8aa3b, v3
	v_pk_add_f32 v[78:79], v[2:3], v[2:3]
	v_exp_f32_e32 v18, v18
	v_fmamk_f32 v3, v79, 0x3c088889, v212
	v_fmaak_f32 v3, v79, v3, 0x3e2aaaab
	v_fma_f32 v3, v79, v3, 0.5
	v_fma_f32 v3, v79, v3, 1.0
	v_mul_f32_e64 v3, v3, -v79
	v_fma_f32 v19, -v18, v18, 1.0
	v_cmp_lt_f32_e64 s[12:13], s22, v79
	v_mul_f32_e32 v2, 0x3fb8aa3b, v2
	v_exp_f32_e32 v2, v2
	v_cndmask_b32_e64 v3, v19, v3, s[12:13]
	v_max_f32_e32 v3, 0, v3
	v_sqrt_f32_e32 v3, v3
	v_cmp_lt_f32_e64 s[0:1], s22, v78
	v_mul_f32_e32 v3, v81, v3
	v_mul_f32_e32 v19, v3, v82
	v_fmamk_f32 v3, v78, 0x3c088889, v212
	v_fmaak_f32 v3, v78, v3, 0x3e2aaaab
	v_fma_f32 v3, v78, v3, 0.5
	v_fma_f32 v3, v78, v3, 1.0
	ds_write_b64 v106, v[18:19] offset:41984
	v_mul_f32_e64 v3, v3, -v78
	v_fma_f32 v18, -v2, v2, 1.0
	v_cndmask_b32_e64 v3, v18, v3, s[0:1]
	v_max_f32_e32 v3, 0, v3
	ds_read_u16 v18, v41 offset:144
	v_sqrt_f32_e32 v3, v3
	s_waitcnt lgkmcnt(0)
; DI float bf2f(u16 v) { return __uint_as_float(((unsigned)v) << 16); }
; DI int crow(int i, int h) { return (i & 3) + 8 * (i >> 2) + 4 * h; }
; DI void lru_item(const Params& p, int l, int b, int chunk, int blk, bool fin, char* smem, int tid) {
;     ...
;       for (int i = 0; i < 16; i++) {
;         const int tok = tb * 32 + crow(i, h);
;         const float rr = __builtin_amdgcn_rcpf(1.f + __expf(-(ga[i] + b_a))), ii = __builtin_amdgcn_rcpf(1.f + __expf(-(gx[i] + b_x)));
;         const float la = -8.f * rr * sp;
;         const float a = __expf(la);
;         const float x2 = 2.f * la;
;         const float ser = -x2 * (1.f + x2 * (0.5f + x2 * (0.16666667f + x2 * (0.041666668f + x2 * 0.0083333338f))));
;         const float om = (x2 > -0.25f) ? ser : (1.f - a * a);
;         const float u = __builtin_amdgcn_sqrtf(fmaxf(om, 0.f)) * ii * bf2f(xcb[tok][chn]);
;         au[(dir * 64 + tok) * 64 + chn] = make_float2(a, u);
;       }
	v_lshlrev_b32_e32 v18, 16, v18
	v_mul_f32_e32 v3, v83, v3
	v_mul_f32_e32 v3, v3, v18
	ds_write_b64 v39, v[2:3] offset:41984
	v_add_f32_e32 v2, v20, v80
	v_mul_f32_e32 v2, 0xbfb8aa3b, v2
	v_exp_f32_e32 v2, v2
	s_nop 0
	v_add_f32_e32 v2, 1.0, v2
	v_rcp_f32_e32 v3, v2
	v_add_f32_e32 v2, v4, v71
	v_mul_f32_e32 v2, 0xbfb8aa3b, v2
	v_exp_f32_e32 v2, v2
	v_add_f32_e32 v4, v5, v71
	v_mul_f32_e32 v4, 0xbfb8aa3b, v4
	v_exp_f32_e32 v4, v4
	v_add_f32_e32 v2, 1.0, v2
	v_rcp_f32_e32 v20, v2
	ds_read_u16 v2, v41 offset:288
	v_add_f32_e32 v4, 1.0, v4
	s_waitcnt lgkmcnt(0)
	v_lshlrev_b32_e32 v78, 16, v2
	v_add_f32_e32 v2, v21, v80
	v_mul_f32_e32 v2, 0xbfb8aa3b, v2
	v_exp_f32_e32 v2, v2
	v_rcp_f32_e32 v21, v4
	v_add_f32_e32 v2, 1.0, v2
	v_rcp_f32_e32 v2, v2
	s_nop 0
	v_pk_mul_f32 v[2:3], v[2:3], s[24:25] op_sel_hi:[1,0]
	s_nop 0
	v_pk_mul_f32 v[2:3], v[2:3], v[0:1] op_sel_hi:[1,0]
	s_nop 0
	v_mul_f32_e32 v4, 0x3fb8aa3b, v3
	v_pk_add_f32 v[18:19], v[2:3], v[2:3]
	v_exp_f32_e32 v4, v4
	v_fmamk_f32 v3, v19, 0x3c088889, v212
	v_fmaak_f32 v3, v19, v3, 0x3e2aaaab
	v_fma_f32 v3, v19, v3, 0.5
	v_fma_f32 v3, v19, v3, 1.0
	v_mul_f32_e64 v3, v3, -v19
	v_fma_f32 v5, -v4, v4, 1.0
	v_cmp_lt_f32_e64 s[12:13], s22, v19
	v_mul_f32_e32 v2, 0x3fb8aa3b, v2
	v_exp_f32_e32 v2, v2
	v_cndmask_b32_e64 v3, v5, v3, s[12:13]
	v_max_f32_e32 v3, 0, v3
	v_sqrt_f32_e32 v3, v3
	v_cmp_lt_f32_e64 s[0:1], s22, v18
	v_mul_f32_e32 v3, v20, v3
	v_mul_f32_e32 v5, v3, v78
	v_fmamk_f32 v3, v18, 0x3c088889, v212
	v_fmaak_f32 v3, v18, v3, 0x3e2aaaab
	v_fma_f32 v3, v18, v3, 0.5
	v_fma_f32 v3, v18, v3, 1.0
	ds_write_b64 v43, v[4:5] offset:41984
	v_mul_f32_e64 v3, v3, -v18
	v_fma_f32 v4, -v2, v2, 1.0
	v_cndmask_b32_e64 v3, v4, v3, s[0:1]
	v_max_f32_e32 v3, 0, v3
	ds_read_u16 v4, v41 offset:432
	v_sqrt_f32_e32 v3, v3
	s_waitcnt lgkmcnt(0)
	v_lshlrev_b32_e32 v4, 16, v4
	v_mul_f32_e32 v3, v21, v3
	v_mul_f32_e32 v3, v3, v4
	ds_write_b64 v61, v[2:3] offset:41984
	v_add_f32_e32 v2, v22, v80
	v_mul_f32_e32 v2, 0xbfb8aa3b, v2
	v_exp_f32_e32 v2, v2
	v_add_f32_e32 v4, v7, v71
	v_mul_f32_e32 v4, 0xbfb8aa3b, v4
	v_exp_f32_e32 v4, v4
	v_add_f32_e32 v2, 1.0, v2
	v_rcp_f32_e32 v3, v2
	v_add_f32_e32 v2, v6, v71
	v_mul_f32_e32 v2, 0xbfb8aa3b, v2
	v_exp_f32_e32 v2, v2
	v_add_f32_e32 v4, 1.0, v4
	v_rcp_f32_e32 v19, v4
	v_add_f32_e32 v2, 1.0, v2
	v_rcp_f32_e32 v5, v2
	ds_read_u16 v2, v41 offset:1152
	s_waitcnt lgkmcnt(0)
	v_lshlrev_b32_e32 v18, 16, v2
	v_add_f32_e32 v2, v23, v80
	v_mul_f32_e32 v2, 0xbfb8aa3b, v2
	v_exp_f32_e32 v2, v2
	s_nop 0
	v_add_f32_e32 v2, 1.0, v2
	v_rcp_f32_e32 v2, v2
	s_nop 0
	v_pk_mul_f32 v[2:3], v[2:3], s[24:25] op_sel_hi:[1,0]
	s_nop 0
	v_pk_mul_f32 v[2:3], v[2:3], v[0:1] op_sel_hi:[1,0]
	s_nop 0
	v_mul_f32_e32 v4, 0x3fb8aa3b, v3
	v_pk_add_f32 v[6:7], v[2:3], v[2:3]
	v_exp_f32_e32 v4, v4
	v_fmamk_f32 v3, v7, 0x3c088889, v212
	v_fmaak_f32 v3, v7, v3, 0x3e2aaaab
	v_fma_f32 v3, v7, v3, 0.5
	v_fma_f32 v3, v7, v3, 1.0
	v_mul_f32_e64 v3, v3, -v7
	v_fma_f32 v20, -v4, v4, 1.0
	v_cmp_lt_f32_e64 s[12:13], s22, v7
	v_mul_f32_e32 v2, 0x3fb8aa3b, v2
	v_exp_f32_e32 v2, v2
	v_cndmask_b32_e64 v3, v20, v3, s[12:13]
	v_max_f32_e32 v3, 0, v3
	v_sqrt_f32_e32 v3, v3
	v_cmp_lt_f32_e64 s[0:1], s22, v6
	v_mul_f32_e32 v3, v5, v3
	v_mul_f32_e32 v5, v3, v18
	v_fmamk_f32 v3, v6, 0x3c088889, v212
	v_fmaak_f32 v3, v6, v3, 0x3e2aaaab
	v_fma_f32 v3, v6, v3, 0.5
	v_fma_f32 v3, v6, v3, 1.0
	ds_write_b64 v94, v[4:5] offset:41984
	v_mul_f32_e64 v3, v3, -v6
	v_fma_f32 v4, -v2, v2, 1.0
	v_cndmask_b32_e64 v3, v4, v3, s[0:1]
	v_max_f32_e32 v3, 0, v3
	ds_read_u16 v4, v41 offset:1296
	v_sqrt_f32_e32 v3, v3
	s_waitcnt lgkmcnt(0)
	v_lshlrev_b32_e32 v4, 16, v4
	v_mul_f32_e32 v3, v19, v3
	v_mul_f32_e32 v3, v3, v4
	ds_write_b64 v95, v[2:3] offset:41984
	v_add_f32_e32 v2, v24, v80
	v_mul_f32_e32 v2, 0xbfb8aa3b, v2
	v_exp_f32_e32 v2, v2
	v_add_f32_e32 v4, v9, v71
	v_mul_f32_e32 v4, 0xbfb8aa3b, v4
	v_exp_f32_e32 v4, v4
	v_add_f32_e32 v2, 1.0, v2
	v_rcp_f32_e32 v3, v2
	v_add_f32_e32 v2, v8, v71
	v_mul_f32_e32 v2, 0xbfb8aa3b, v2
	v_exp_f32_e32 v2, v2
	v_add_f32_e32 v4, 1.0, v4
	v_rcp_f32_e32 v9, v4
	v_add_f32_e32 v2, 1.0, v2
	v_rcp_f32_e32 v5, v2
	ds_read_u16 v2, v41 offset:1440
	s_waitcnt lgkmcnt(0)
	v_lshlrev_b32_e32 v8, 16, v2
	v_add_f32_e32 v2, v25, v80
	v_mul_f32_e32 v2, 0xbfb8aa3b, v2
	v_exp_f32_e32 v2, v2
	s_nop 0
	v_add_f32_e32 v2, 1.0, v2
	v_rcp_f32_e32 v2, v2
	s_nop 0
	v_pk_mul_f32 v[2:3], v[2:3], s[24:25] op_sel_hi:[1,0]
	s_nop 0
	v_pk_mul_f32 v[2:3], v[2:3], v[0:1] op_sel_hi:[1,0]
	s_nop 0
	v_mul_f32_e32 v4, 0x3fb8aa3b, v3
	v_pk_add_f32 v[6:7], v[2:3], v[2:3]
	v_exp_f32_e32 v4, v4
	v_fmamk_f32 v3, v7, 0x3c088889, v212
	v_fmaak_f32 v3, v7, v3, 0x3e2aaaab
	v_fma_f32 v3, v7, v3, 0.5
	v_fma_f32 v3, v7, v3, 1.0
	v_mul_f32_e64 v3, v3, -v7
	v_fma_f32 v18, -v4, v4, 1.0
	v_cmp_lt_f32_e64 s[12:13], s22, v7
	v_mul_f32_e32 v2, 0x3fb8aa3b, v2
	v_exp_f32_e32 v2, v2
	v_cndmask_b32_e64 v3, v18, v3, s[12:13]
	v_max_f32_e32 v3, 0, v3
	v_sqrt_f32_e32 v3, v3
	v_cmp_lt_f32_e64 s[0:1], s22, v6
	v_mul_f32_e32 v3, v5, v3
	v_mul_f32_e32 v5, v3, v8
	v_fmamk_f32 v3, v6, 0x3c088889, v212
	v_fmaak_f32 v3, v6, v3, 0x3e2aaaab
	v_fma_f32 v3, v6, v3, 0.5
	v_fma_f32 v3, v6, v3, 1.0
	ds_write_b64 v96, v[4:5] offset:41984
	v_mul_f32_e64 v3, v3, -v6
	v_fma_f32 v4, -v2, v2, 1.0
	v_cndmask_b32_e64 v3, v4, v3, s[0:1]
	v_max_f32_e32 v3, 0, v3
	ds_read_u16 v4, v41 offset:1584
	v_sqrt_f32_e32 v3, v3
	s_waitcnt lgkmcnt(0)
; DI float bf2f(u16 v) { return __uint_as_float(((unsigned)v) << 16); }
; DI int crow(int i, int h) { return (i & 3) + 8 * (i >> 2) + 4 * h; }
; DI void lru_item(const Params& p, int l, int b, int chunk, int blk, bool fin, char* smem, int tid) {
;     ...
;       for (int i = 0; i < 16; i++) {
;         const int tok = tb * 32 + crow(i, h);
;         const float rr = __builtin_amdgcn_rcpf(1.f + __expf(-(ga[i] + b_a))), ii = __builtin_amdgcn_rcpf(1.f + __expf(-(gx[i] + b_x)));
;         const float la = -8.f * rr * sp;
;         const float a = __expf(la);
;         const float x2 = 2.f * la;
;         const float ser = -x2 * (1.f + x2 * (0.5f + x2 * (0.16666667f + x2 * (0.041666668f + x2 * 0.0083333338f))));
;         const float om = (x2 > -0.25f) ? ser : (1.f - a * a);
;         const float u = __builtin_amdgcn_sqrtf(fmaxf(om, 0.f)) * ii * bf2f(xcb[tok][chn]);
;         au[(dir * 64 + tok) * 64 + chn] = make_float2(a, u);
;       }
	v_lshlrev_b32_e32 v4, 16, v4
	v_mul_f32_e32 v3, v9, v3
	v_mul_f32_e32 v3, v3, v4
	ds_write_b64 v97, v[2:3] offset:41984
	v_add_f32_e32 v2, v26, v80
	v_mul_f32_e32 v2, 0xbfb8aa3b, v2
	v_exp_f32_e32 v2, v2
	v_add_f32_e32 v4, v11, v71
	v_mul_f32_e32 v4, 0xbfb8aa3b, v4
	v_exp_f32_e32 v4, v4
	v_add_f32_e32 v2, 1.0, v2
	v_rcp_f32_e32 v3, v2
	v_add_f32_e32 v2, v10, v71
	v_mul_f32_e32 v2, 0xbfb8aa3b, v2
	v_exp_f32_e32 v2, v2
	v_add_f32_e32 v4, 1.0, v4
	v_rcp_f32_e32 v9, v4
	v_add_f32_e32 v2, 1.0, v2
	v_rcp_f32_e32 v5, v2
	ds_read_u16 v2, v41 offset:2304
	s_waitcnt lgkmcnt(0)
	v_lshlrev_b32_e32 v8, 16, v2
	v_add_f32_e32 v2, v27, v80
	v_mul_f32_e32 v2, 0xbfb8aa3b, v2
	v_exp_f32_e32 v2, v2
	s_nop 0
	v_add_f32_e32 v2, 1.0, v2
	v_rcp_f32_e32 v2, v2
	s_nop 0
	v_pk_mul_f32 v[2:3], v[2:3], s[24:25] op_sel_hi:[1,0]
	s_nop 0
	v_pk_mul_f32 v[2:3], v[2:3], v[0:1] op_sel_hi:[1,0]
	s_nop 0
	v_mul_f32_e32 v4, 0x3fb8aa3b, v3
	v_pk_add_f32 v[6:7], v[2:3], v[2:3]
	v_exp_f32_e32 v4, v4
	v_fmamk_f32 v3, v7, 0x3c088889, v212
	v_fmaak_f32 v3, v7, v3, 0x3e2aaaab
	v_fma_f32 v3, v7, v3, 0.5
	v_fma_f32 v3, v7, v3, 1.0
	v_mul_f32_e64 v3, v3, -v7
	v_fma_f32 v10, -v4, v4, 1.0
	v_cmp_lt_f32_e64 s[12:13], s22, v7
	v_mul_f32_e32 v2, 0x3fb8aa3b, v2
	v_exp_f32_e32 v2, v2
	v_cndmask_b32_e64 v3, v10, v3, s[12:13]
	v_max_f32_e32 v3, 0, v3
	v_sqrt_f32_e32 v3, v3
	v_cmp_lt_f32_e64 s[0:1], s22, v6
	v_mul_f32_e32 v3, v5, v3
	v_mul_f32_e32 v5, v3, v8
	v_fmamk_f32 v3, v6, 0x3c088889, v212
	v_fmaak_f32 v3, v6, v3, 0x3e2aaaab
	v_fma_f32 v3, v6, v3, 0.5
	v_fma_f32 v3, v6, v3, 1.0
	ds_write_b64 v98, v[4:5] offset:41984
	v_mul_f32_e64 v3, v3, -v6
	v_fma_f32 v4, -v2, v2, 1.0
	v_cndmask_b32_e64 v3, v4, v3, s[0:1]
	v_max_f32_e32 v3, 0, v3
	ds_read_u16 v4, v41 offset:2448
	v_sqrt_f32_e32 v3, v3
	s_waitcnt lgkmcnt(0)
	v_lshlrev_b32_e32 v4, 16, v4
	v_mul_f32_e32 v3, v9, v3
	v_mul_f32_e32 v3, v3, v4
	ds_write_b64 v99, v[2:3] offset:41984
	v_add_f32_e32 v2, v28, v80
	v_mul_f32_e32 v2, 0xbfb8aa3b, v2
	v_exp_f32_e32 v2, v2
	v_add_f32_e32 v4, v13, v71
	v_mul_f32_e32 v4, 0xbfb8aa3b, v4
	v_exp_f32_e32 v4, v4
	v_add_f32_e32 v2, 1.0, v2
	v_rcp_f32_e32 v3, v2
	v_add_f32_e32 v2, v12, v71
	v_mul_f32_e32 v2, 0xbfb8aa3b, v2
	v_exp_f32_e32 v2, v2
	v_add_f32_e32 v4, 1.0, v4
	v_rcp_f32_e32 v9, v4
	v_add_f32_e32 v2, 1.0, v2
	v_rcp_f32_e32 v5, v2
	ds_read_u16 v2, v41 offset:2592
	s_waitcnt lgkmcnt(0)
	v_lshlrev_b32_e32 v8, 16, v2
	v_add_f32_e32 v2, v29, v80
	v_mul_f32_e32 v2, 0xbfb8aa3b, v2
	v_exp_f32_e32 v2, v2
	s_nop 0
	v_add_f32_e32 v2, 1.0, v2
	v_rcp_f32_e32 v2, v2
	s_nop 0
	v_pk_mul_f32 v[2:3], v[2:3], s[24:25] op_sel_hi:[1,0]
	s_nop 0
	v_pk_mul_f32 v[2:3], v[2:3], v[0:1] op_sel_hi:[1,0]
	s_nop 0
	v_mul_f32_e32 v4, 0x3fb8aa3b, v3
	v_pk_add_f32 v[6:7], v[2:3], v[2:3]
	v_exp_f32_e32 v4, v4
	v_fmamk_f32 v3, v7, 0x3c088889, v212
	v_fmaak_f32 v3, v7, v3, 0x3e2aaaab
	v_fma_f32 v3, v7, v3, 0.5
	v_fma_f32 v3, v7, v3, 1.0
	v_mul_f32_e64 v3, v3, -v7
	v_fma_f32 v10, -v4, v4, 1.0
	v_cmp_lt_f32_e64 s[12:13], s22, v7
	v_mul_f32_e32 v2, 0x3fb8aa3b, v2
	v_exp_f32_e32 v2, v2
	v_cndmask_b32_e64 v3, v10, v3, s[12:13]
	v_max_f32_e32 v3, 0, v3
	v_sqrt_f32_e32 v3, v3
	v_cmp_lt_f32_e64 s[0:1], s22, v6
	v_mul_f32_e32 v3, v5, v3
	v_mul_f32_e32 v5, v3, v8
	v_fmamk_f32 v3, v6, 0x3c088889, v212
	v_fmaak_f32 v3, v6, v3, 0x3e2aaaab
	v_fma_f32 v3, v6, v3, 0.5
	v_fma_f32 v3, v6, v3, 1.0
	ds_write_b64 v100, v[4:5] offset:41984
	v_mul_f32_e64 v3, v3, -v6
	v_fma_f32 v4, -v2, v2, 1.0
	v_cndmask_b32_e64 v3, v4, v3, s[0:1]
	v_max_f32_e32 v3, 0, v3
	ds_read_u16 v4, v41 offset:2736
	v_sqrt_f32_e32 v3, v3
	s_waitcnt lgkmcnt(0)
	v_lshlrev_b32_e32 v4, 16, v4
	v_mul_f32_e32 v3, v9, v3
	v_mul_f32_e32 v3, v3, v4
	ds_write_b64 v101, v[2:3] offset:41984
	v_add_f32_e32 v2, v30, v80
	v_mul_f32_e32 v2, 0xbfb8aa3b, v2
	v_exp_f32_e32 v2, v2
	v_add_f32_e32 v4, v15, v71
	v_mul_f32_e32 v4, 0xbfb8aa3b, v4
	v_exp_f32_e32 v4, v4
	v_add_f32_e32 v2, 1.0, v2
	v_rcp_f32_e32 v3, v2
	v_add_f32_e32 v2, v14, v71
	v_mul_f32_e32 v2, 0xbfb8aa3b, v2
	v_exp_f32_e32 v2, v2
	v_add_f32_e32 v4, 1.0, v4
	v_rcp_f32_e32 v9, v4
	v_add_f32_e32 v2, 1.0, v2
	v_rcp_f32_e32 v5, v2
	ds_read_u16 v2, v41 offset:3456
	s_waitcnt lgkmcnt(0)
; DI void lru_item(const Params& p, int l, int b, int chunk, int blk, bool fin, char* smem, int tid) {
;     ...
;         au[(dir * 64 + tok) * 64 + chn] = make_float2(a, u);
;       }
;     }
;   }
;   __syncthreads();
;   float2* agg = (float2*)p.agg;
;   if (w < 2) {
;     const int dir = w, ch = lane;
;     float hst = 0.f;
;     if (!fin) {
;       float Ap = 1.f;
; #pragma unroll 8
;       for (int s2 = 0; s2 < 64; s2++) { const int t = dir ? 63 - s2 : s2; float2 v = au[(dir * 64 + t) * 64 + ch]; hst = v.x * hst + v.y; Ap *= v.x; }
;       agg[(((size_t)b * 68 + chunk) * 2 + dir) * 256 + c0 + ch] = make_float2(Ap, hst);
;     } else {
;       const float2* ag = agg + ((size_t)b * 68 * 2 + dir) * 256 + c0 + ch;
;       if (dir == 0) {
; #pragma unroll 8
;         for (int cc = 0; cc < chunk; cc++) { float2 v = ag[(size_t)cc * 512]; hst = v.x * hst + v.y; }
	v_lshlrev_b32_e32 v8, 16, v2
	v_add_f32_e32 v2, v31, v80
	v_mul_f32_e32 v2, 0xbfb8aa3b, v2
	v_exp_f32_e32 v2, v2
	s_nop 0
	v_add_f32_e32 v2, 1.0, v2
	v_rcp_f32_e32 v2, v2
	s_nop 0
	v_pk_mul_f32 v[2:3], v[2:3], s[24:25] op_sel_hi:[1,0]
	s_nop 0
	v_pk_mul_f32 v[2:3], v[2:3], v[0:1] op_sel_hi:[1,0]
	s_nop 0
	v_mul_f32_e32 v4, 0x3fb8aa3b, v3
	v_pk_add_f32 v[6:7], v[2:3], v[2:3]
	v_exp_f32_e32 v4, v4
	v_fmamk_f32 v3, v7, 0x3c088889, v212
	v_fmaak_f32 v3, v7, v3, 0x3e2aaaab
	v_fma_f32 v3, v7, v3, 0.5
	v_fma_f32 v3, v7, v3, 1.0
	v_mul_f32_e64 v3, v3, -v7
	v_fma_f32 v10, -v4, v4, 1.0
	v_cmp_lt_f32_e64 s[12:13], s22, v7
	v_mul_f32_e32 v2, 0x3fb8aa3b, v2
	v_exp_f32_e32 v2, v2
	v_cndmask_b32_e64 v3, v10, v3, s[12:13]
	v_max_f32_e32 v3, 0, v3
	v_sqrt_f32_e32 v3, v3
	v_cmp_lt_f32_e64 s[0:1], s22, v6
	v_mul_f32_e32 v3, v5, v3
	v_mul_f32_e32 v5, v3, v8
	v_fmamk_f32 v3, v6, 0x3c088889, v212
	v_fmaak_f32 v3, v6, v3, 0x3e2aaaab
	v_fma_f32 v3, v6, v3, 0.5
	v_fma_f32 v3, v6, v3, 1.0
	ds_write_b64 v102, v[4:5] offset:41984
	v_mul_f32_e64 v3, v3, -v6
	v_fma_f32 v4, -v2, v2, 1.0
	v_cndmask_b32_e64 v3, v4, v3, s[0:1]
	v_max_f32_e32 v3, 0, v3
	ds_read_u16 v4, v41 offset:3600
	v_sqrt_f32_e32 v3, v3
	s_waitcnt lgkmcnt(0)
	v_lshlrev_b32_e32 v4, 16, v4
	v_mul_f32_e32 v3, v9, v3
	v_mul_f32_e32 v3, v3, v4
	ds_write_b64 v103, v[2:3] offset:41984
	v_add_f32_e32 v2, v32, v80
	v_mul_f32_e32 v2, 0xbfb8aa3b, v2
	v_exp_f32_e32 v2, v2
	v_add_f32_e32 v4, v17, v71
	v_mul_f32_e32 v4, 0xbfb8aa3b, v4
	v_exp_f32_e32 v4, v4
	v_add_f32_e32 v2, 1.0, v2
	v_rcp_f32_e32 v3, v2
	v_add_f32_e32 v2, v16, v71
	v_mul_f32_e32 v2, 0xbfb8aa3b, v2
	v_exp_f32_e32 v2, v2
	v_add_f32_e32 v4, 1.0, v4
	v_rcp_f32_e32 v9, v4
	v_add_f32_e32 v2, 1.0, v2
	v_rcp_f32_e32 v5, v2
	ds_read_u16 v2, v41 offset:3744
	s_waitcnt lgkmcnt(0)
	v_lshlrev_b32_e32 v8, 16, v2
	v_add_f32_e32 v2, v33, v80
	v_mul_f32_e32 v2, 0xbfb8aa3b, v2
	v_exp_f32_e32 v2, v2
	s_nop 0
	v_add_f32_e32 v2, 1.0, v2
	v_rcp_f32_e32 v2, v2
	s_nop 0
	v_pk_mul_f32 v[2:3], v[2:3], s[24:25] op_sel_hi:[1,0]
	s_nop 0
	v_pk_mul_f32 v[2:3], v[2:3], v[0:1] op_sel_hi:[1,0]
	s_nop 0
	v_mul_f32_e32 v0, 0x3fb8aa3b, v3
	v_pk_add_f32 v[6:7], v[2:3], v[2:3]
	v_exp_f32_e32 v4, v0
	v_fmamk_f32 v0, v7, 0x3c088889, v212
	v_fmaak_f32 v0, v7, v0, 0x3e2aaaab
	v_fma_f32 v0, v7, v0, 0.5
	v_fma_f32 v0, v7, v0, 1.0
	v_mul_f32_e64 v0, v0, -v7
	v_fma_f32 v3, -v4, v4, 1.0
	v_cmp_lt_f32_e64 s[12:13], s22, v7
	v_cmp_lt_f32_e64 s[0:1], s22, v6
	s_nop 0
	v_cndmask_b32_e64 v0, v3, v0, s[12:13]
	v_max_f32_e32 v0, 0, v0
	v_sqrt_f32_e32 v0, v0
	s_nop 0
	v_mul_f32_e32 v0, v5, v0
	v_mul_f32_e32 v5, v0, v8
	v_mul_f32_e32 v0, 0x3fb8aa3b, v2
	v_exp_f32_e32 v2, v0
	v_fmamk_f32 v0, v6, 0x3c088889, v212
	v_fmaak_f32 v0, v6, v0, 0x3e2aaaab
	v_fma_f32 v0, v6, v0, 0.5
	v_fma_f32 v0, v6, v0, 1.0
	v_mul_f32_e64 v0, v0, -v6
	v_fma_f32 v3, -v2, v2, 1.0
	ds_write_b64 v104, v[4:5] offset:41984
	v_cndmask_b32_e64 v0, v3, v0, s[0:1]
	v_max_f32_e32 v0, 0, v0
	ds_read_u16 v3, v41 offset:3888
	v_sqrt_f32_e32 v0, v0
	s_waitcnt lgkmcnt(0)
	v_lshlrev_b32_e32 v3, 16, v3
	v_mul_f32_e32 v0, v9, v0
	v_mul_f32_e32 v3, v0, v3
	ds_write_b64 v105, v[2:3] offset:41984
	s_waitcnt lgkmcnt(0)
	s_barrier
	s_and_saveexec_b64 s[0:1], s[4:5]
	s_cbranch_execz .LBB0_1085
	v_lshrrev_b32_e32 v0, 6, v206
	v_and_b32_e32 v2, 63, v206
	v_readfirstlane_b32 s20, v77
	v_readfirstlane_b32 s21, v73
	v_readfirstlane_b32 s22, v74
	v_readfirstlane_b32 s23, v0
	v_lshlrev_b32_e32 v2, 3, v2
	v_readlane_b32 s2, v253, 44
	v_readlane_b32 s3, v253, 45
	s_mul_i32 s12, s21, 0x88
	s_add_u32 s12, s12, s23
	s_lshl_b32 s12, s12, 11
	s_lshl_b32 s13, s22, 3
	s_add_u32 s12, s12, s13
	s_add_u32 s2, s2, s12
	s_addc_u32 s3, s3, 0
	v_mov_b32_e32 v5, 0
	s_cmp_eq_u32 s23, 0
	s_cbranch_scc0 .Llf_dir1
	s_mov_b32 s24, 0x1000
	s_mov_b32 s25, 0
	s_mov_b32 s26, s2
	s_mov_b32 s27, s3
	s_mov_b32 s12, s20
	s_mov_b32 s13, 0
	s_branch .Llf_run
